# 7.3 widened stores in P3 K-tile epilogue (g/g+1 pairs via v_permlane32_swap -> 8 dwordx4 per lane) on top of early-invalidate barrier + V-tile widening
# speedup vs baseline: 1.0214x; 1.0019x over previous
; template <bool SWAP, class Epi>
; DI void gemm_tile(const u16* __restrict__ A, int lda, const u16* __restrict__ Bt, int ldb, int K, int m0, int n0, char* smem, Epi&& epi) {
;     ...
;   const int srow = tid >> 3, skc = tid & 7;
;   const u16* ag = A + (size_t)(m0 + srow) * lda + skc * 8;
;   const u16* bg = Bt + (size_t)(n0 + srow) * ldb + skc * 8;
;   u16* asw = As + srow * 72 + skc * 8;
;   u16* bsw = Bs + srow * 72 + skc * 8;
;   u32x4 ra0[4], rb0[4], ra1[4], rb1[4];
; #pragma unroll
;   for (int i = 0; i < 4; ++i) { ra0[i] = *(const u32x4*)(ag + (size_t)i * 32 * lda); rb0[i] = *(const u32x4*)(bg + (size_t)i * 32 * ldb); }
; #pragma unroll
;   for (int i = 0; i < 4; ++i) { ra1[i] = *(const u32x4*)(ag + (size_t)i * 32 * lda + 64); rb1[i] = *(const u32x4*)(bg + (size_t)i * 32 * ldb + 64); }
;   __syncthreads();
; #pragma unroll
;   for (int i = 0; i < 4; ++i) { *(u32x4*)(asw + 32 * i * 72) = ra0[i]; *(u32x4*)(bsw + 32 * i * 72) = rb0[i]; }
;   __syncthreads();
;   const int KT = K >> 6;
;   const u16* Asb = As + (wm * 64 + r) * 72 + hi * 8;
;   const u16* Bsb = Bs + (wn * 64 + r) * 72 + hi * 8;
;   auto compute = [&](int buf) __attribute__((always_inline)) {
;     bf16x8 af[2][2], bfr[2][2];
;     af[0][0] = *(const bf16x8*)(Asb + buf * 128 * 72);
;     af[0][1] = *(const bf16x8*)(Asb + buf * 128 * 72 + 32 * 72);
;     bfr[0][0] = *(const bf16x8*)(Bsb + buf * 128 * 72);
;     bfr[0][1] = *(const bf16x8*)(Bsb + buf * 128 * 72 + 32 * 72);
; #pragma unroll
;     for (int ks = 0; ks < 4; ++ks) {
;       const int c = ks & 1, n = c ^ 1;
;       if (ks < 3) {
;         af[n][0] = *(const bf16x8*)(Asb + buf * 128 * 72 + (ks + 1) * 16);
;         af[n][1] = *(const bf16x8*)(Asb + buf * 128 * 72 + 32 * 72 + (ks + 1) * 16);
;         bfr[n][0] = *(const bf16x8*)(Bsb + buf * 128 * 72 + (ks + 1) * 16);
;         bfr[n][1] = *(const bf16x8*)(Bsb + buf * 128 * 72 + 32 * 72 + (ks + 1) * 16);
;       }
;       __builtin_amdgcn_sched_barrier(0);
; #pragma unroll
;       for (int mi = 0; mi < 2; ++mi)
; #pragma unroll
;         for (int ni = 0; ni < 2; ++ni) {
;           if (SWAP) acc[mi][ni] = MFMA(bfr[c][ni], af[c][mi], acc[mi][ni]);
;           else acc[mi][ni] = MFMA(af[c][mi], bfr[c][ni], acc[mi][ni]);
;         }
;       __builtin_amdgcn_sched_barrier(0);
;     }
;   };
;   for (int kt = 0; kt < KT; kt += 2) {
;     if (kt + 2 < KT) {
;       const int k0 = (kt + 2) << 6;
.LBB0_513:
	s_andn2_b64 vcc, exec, s[50:51]
	s_cbranch_vccnz .LBB0_515
	global_load_dwordx4 v[2:5], v[80:81], off
	global_load_dwordx4 v[6:9], v[82:83], off
	global_load_dwordx4 v[10:13], v[90:91], off
	global_load_dwordx4 v[14:17], v[106:107], off
	global_load_dwordx4 v[18:21], v[88:89], off
	global_load_dwordx4 v[22:25], v[104:105], off
	global_load_dwordx4 v[26:29], v[86:87], off
	global_load_dwordx4 v[30:33], v[102:103], off
	s_nop 0
	global_load_dwordx4 v[102:105], v[80:81], off offset:128
	global_load_dwordx4 v[106:109], v[82:83], off offset:128
	global_load_dwordx4 v[110:113], v[84:85], off
	global_load_dwordx4 v[114:117], v[92:93], off
	global_load_dwordx4 v[140:143], v[94:95], off
	global_load_dwordx4 v[144:147], v[96:97], off
	s_nop 0
	global_load_dwordx4 v[96:99], v[98:99], off
	s_nop 0
	global_load_dwordx4 v[148:151], v[100:101], off
	v_add_co_u32_e32 v84, vcc, s67, v80
	s_waitcnt lgkmcnt(0)
	s_nop 0
	v_addc_co_u32_e32 v85, vcc, 0, v81, vcc
	v_add_co_u32_e32 v86, vcc, s70, v82
	s_barrier
	s_nop 0
	v_addc_co_u32_e32 v87, vcc, 0, v83, vcc
	v_add_co_u32_e32 v88, vcc, s71, v80
	s_nop 1
	v_addc_co_u32_e32 v89, vcc, 0, v81, vcc
	v_add_co_u32_e32 v90, vcc, s72, v82
	s_waitcnt vmcnt(15)
	ds_write_b128 v121, v[2:5] offset:16
	s_waitcnt vmcnt(14)
	ds_write_b128 v121, v[6:9] offset:36880
	s_waitcnt vmcnt(13)
	ds_write_b128 v121, v[10:13] offset:4624
	s_waitcnt vmcnt(12)
	ds_write_b128 v121, v[14:17] offset:41488
	s_waitcnt vmcnt(11)
	ds_write_b128 v121, v[18:21] offset:9232
	s_waitcnt vmcnt(10)
	ds_write_b128 v121, v[22:25] offset:46096
	s_waitcnt vmcnt(9)
	ds_write_b128 v121, v[26:29] offset:13840
	s_waitcnt vmcnt(8)
	ds_write_b128 v121, v[30:33] offset:50704
	v_addc_co_u32_e32 v91, vcc, 0, v83, vcc
	v_add_co_u32_e32 v92, vcc, s73, v80
	s_waitcnt lgkmcnt(0)
	s_nop 0
	v_addc_co_u32_e32 v93, vcc, 0, v81, vcc
	v_add_co_u32_e32 v94, vcc, s62, v82
	s_barrier
	s_nop 0
	v_addc_co_u32_e32 v95, vcc, 0, v83, vcc
	global_load_dwordx4 v[152:155], v[80:81], off offset:256
	global_load_dwordx4 v[156:159], v[82:83], off offset:256
	global_load_dwordx4 v[160:163], v[84:85], off offset:256
	global_load_dwordx4 v[164:167], v[86:87], off offset:256
	global_load_dwordx4 v[168:171], v[88:89], off offset:256
	global_load_dwordx4 v[172:175], v[90:91], off offset:256
	global_load_dwordx4 v[176:179], v[92:93], off offset:256
	global_load_dwordx4 v[180:183], v[94:95], off offset:256
	ds_read_b128 v[2:5], v124 offset:16
	ds_read_b128 v[184:187], v124 offset:48
	ds_read_b128 v[6:9], v124 offset:4624
	ds_read_b128 v[190:193], v124 offset:4656
	ds_read_b128 v[10:13], v126 offset:36880
	ds_read_b128 v[194:197], v126 offset:36912
	ds_read_b128 v[14:17], v126 offset:41488
	ds_read_b128 v[198:201], v126 offset:41520
	s_waitcnt lgkmcnt(3)
	v_mfma_f32_32x32x16_bf16 v[50:65], v[10:13], v[2:5], 0
	s_waitcnt lgkmcnt(1)
	v_mfma_f32_32x32x16_bf16 v[34:49], v[14:17], v[2:5], 0
	v_mfma_f32_32x32x16_bf16 v[18:33], v[10:13], v[6:9], 0
	v_mfma_f32_32x32x16_bf16 v[2:17], v[14:17], v[6:9], 0
	ds_read_b128 v[202:205], v124 offset:80
	ds_read_b128 v[206:209], v124 offset:4688
	ds_read_b128 v[210:213], v126 offset:36944
	ds_read_b128 v[214:217], v126 offset:41552
	s_waitcnt lgkmcnt(4)
	v_mfma_f32_32x32x16_bf16 v[2:17], v[198:201], v[190:193], v[2:17]
	v_mfma_f32_32x32x16_bf16 v[50:65], v[194:197], v[184:187], v[50:65]
	v_mfma_f32_32x32x16_bf16 v[34:49], v[198:201], v[184:187], v[34:49]
	v_mfma_f32_32x32x16_bf16 v[18:33], v[194:197], v[190:193], v[18:33]
	ds_read_b128 v[184:187], v124 offset:112
	ds_read_b128 v[190:193], v124 offset:4720
	ds_read_b128 v[194:197], v126 offset:36976
	ds_read_b128 v[198:201], v126 offset:41584
	s_waitcnt lgkmcnt(4)
	v_mfma_f32_32x32x16_bf16 v[2:17], v[214:217], v[206:209], v[2:17]
	v_mfma_f32_32x32x16_bf16 v[50:65], v[210:213], v[202:205], v[50:65]
	v_mfma_f32_32x32x16_bf16 v[34:49], v[214:217], v[202:205], v[34:49]
	v_mfma_f32_32x32x16_bf16 v[18:33], v[210:213], v[206:209], v[18:33]
	s_waitcnt lgkmcnt(0)
	v_mfma_f32_32x32x16_bf16 v[2:17], v[198:201], v[190:193], v[2:17]
	v_mfma_f32_32x32x16_bf16 v[50:65], v[194:197], v[184:187], v[50:65]
	v_mfma_f32_32x32x16_bf16 v[34:49], v[198:201], v[184:187], v[34:49]
	v_mfma_f32_32x32x16_bf16 v[18:33], v[194:197], v[190:193], v[18:33]
	s_waitcnt vmcnt(15)
	ds_write_b128 v121, v[102:105] offset:18448
	s_waitcnt vmcnt(14)
	ds_write_b128 v121, v[106:109] offset:55312
	s_waitcnt vmcnt(13)
	ds_write_b128 v121, v[110:113] offset:23056
	s_waitcnt vmcnt(12)
	ds_write_b128 v121, v[114:117] offset:59920
	s_waitcnt vmcnt(11)
	ds_write_b128 v121, v[140:143] offset:27664
	s_waitcnt vmcnt(10)
	ds_write_b128 v121, v[144:147] offset:64528
	s_waitcnt vmcnt(9)
	ds_write_b128 v121, v[96:99] offset:32272
	s_waitcnt vmcnt(8)
	ds_write_b128 v122, v[148:151] offset:32256
	s_waitcnt lgkmcnt(0)
	s_barrier
; template <bool SWAP, class Epi>
; DI void gemm_tile(const u16* __restrict__ A, int lda, const u16* __restrict__ Bt, int ldb, int K, int m0, int n0, char* smem, Epi&& epi) {
;     ...
;   for (int kt = 0; kt < KT; kt += 2) {
;     if (kt + 2 < KT) {
;       const int k0 = (kt + 2) << 6;
; #pragma unroll
;       for (int i = 0; i < 4; ++i) { ra0[i] = *(const u32x4*)(ag + (size_t)i * 32 * lda + k0); rb0[i] = *(const u32x4*)(bg + (size_t)i * 32 * ldb + k0); }
;     }
;     compute(0);
; #pragma unroll
;     for (int i = 0; i < 4; ++i) { *(u32x4*)(asw + 128 * 72 + 32 * i * 72) = ra1[i]; *(u32x4*)(bsw + 128 * 72 + 32 * i * 72) = rb1[i]; }
;     __syncthreads();
;     if (kt + 3 < KT) {
;       const int k0 = (kt + 3) << 6;
; #pragma unroll
;       for (int i = 0; i < 4; ++i) { ra1[i] = *(const u32x4*)(ag + (size_t)i * 32 * lda + k0); rb1[i] = *(const u32x4*)(bg + (size_t)i * 32 * ldb + k0); }
;     }
;     compute(1);
;     if (kt + 2 < KT) {
; #pragma unroll
;       for (int i = 0; i < 4; ++i) { *(u32x4*)(asw + 32 * i * 72) = ra0[i]; *(u32x4*)(bsw + 32 * i * 72) = rb0[i]; }
;     }
;     __syncthreads();
	global_load_dwordx4 v[96:99], v[80:81], off offset:384
	global_load_dwordx4 v[100:103], v[82:83], off offset:384
	global_load_dwordx4 v[104:107], v[84:85], off offset:384
	global_load_dwordx4 v[108:111], v[86:87], off offset:384
	global_load_dwordx4 v[112:115], v[88:89], off offset:384
	global_load_dwordx4 v[116:119], v[90:91], off offset:384
	global_load_dwordx4 v[140:143], v[92:93], off offset:384
	global_load_dwordx4 v[144:147], v[94:95], off offset:384
	ds_read_b128 v[148:151], v124 offset:18448
	ds_read_b128 v[184:187], v124 offset:18480
	ds_read_b128 v[190:193], v124 offset:23056
	ds_read_b128 v[194:197], v124 offset:23088
	ds_read_b128 v[198:201], v126 offset:55312
	ds_read_b128 v[202:205], v126 offset:55344
	ds_read_b128 v[206:209], v126 offset:59920
	ds_read_b128 v[210:213], v126 offset:59952
	s_waitcnt lgkmcnt(1)
	v_mfma_f32_32x32x16_bf16 v[2:17], v[206:209], v[190:193], v[2:17]
	v_mfma_f32_32x32x16_bf16 v[50:65], v[198:201], v[148:151], v[50:65]
	v_mfma_f32_32x32x16_bf16 v[34:49], v[206:209], v[148:151], v[34:49]
	v_mfma_f32_32x32x16_bf16 v[18:33], v[198:201], v[190:193], v[18:33]
	ds_read_b128 v[148:151], v124 offset:18512
	ds_read_b128 v[190:193], v124 offset:23120
	ds_read_b128 v[198:201], v126 offset:55376
	ds_read_b128 v[206:209], v126 offset:59984
	s_waitcnt lgkmcnt(4)
	v_mfma_f32_32x32x16_bf16 v[2:17], v[210:213], v[194:197], v[2:17]
	v_mfma_f32_32x32x16_bf16 v[50:65], v[202:205], v[184:187], v[50:65]
	v_mfma_f32_32x32x16_bf16 v[34:49], v[210:213], v[184:187], v[34:49]
	v_mfma_f32_32x32x16_bf16 v[18:33], v[202:205], v[194:197], v[18:33]
	ds_read_b128 v[184:187], v124 offset:18544
	ds_read_b128 v[194:197], v124 offset:23152
	ds_read_b128 v[202:205], v126 offset:55408
	ds_read_b128 v[210:213], v126 offset:60016
	s_waitcnt lgkmcnt(4)
	v_mfma_f32_32x32x16_bf16 v[2:17], v[206:209], v[190:193], v[2:17]
	v_mfma_f32_32x32x16_bf16 v[50:65], v[198:201], v[148:151], v[50:65]
	v_mfma_f32_32x32x16_bf16 v[34:49], v[206:209], v[148:151], v[34:49]
	v_mfma_f32_32x32x16_bf16 v[18:33], v[198:201], v[190:193], v[18:33]
	s_waitcnt lgkmcnt(0)
	v_mfma_f32_32x32x16_bf16 v[2:17], v[210:213], v[194:197], v[2:17]
	v_mfma_f32_32x32x16_bf16 v[50:65], v[202:205], v[184:187], v[50:65]
	v_mfma_f32_32x32x16_bf16 v[34:49], v[210:213], v[184:187], v[34:49]
	v_mfma_f32_32x32x16_bf16 v[18:33], v[202:205], v[194:197], v[18:33]
	s_waitcnt vmcnt(15)
	ds_write_b128 v121, v[152:155] offset:16
	s_waitcnt vmcnt(14)
	ds_write_b128 v121, v[156:159] offset:36880
	s_waitcnt vmcnt(13)
	ds_write_b128 v121, v[160:163] offset:4624
	s_waitcnt vmcnt(12)
	ds_write_b128 v121, v[164:167] offset:41488
	s_waitcnt vmcnt(11)
	ds_write_b128 v121, v[168:171] offset:9232
	s_waitcnt vmcnt(10)
	ds_write_b128 v121, v[172:175] offset:46096
	s_waitcnt vmcnt(9)
	ds_write_b128 v121, v[176:179] offset:13840
	s_waitcnt vmcnt(8)
	ds_write_b128 v121, v[180:183] offset:50704
	s_waitcnt lgkmcnt(0)
	s_barrier
	global_load_dwordx4 v[148:151], v[80:81], off offset:512
	global_load_dwordx4 v[152:155], v[82:83], off offset:512
	global_load_dwordx4 v[156:159], v[84:85], off offset:512
	global_load_dwordx4 v[160:163], v[86:87], off offset:512
	global_load_dwordx4 v[164:167], v[88:89], off offset:512
	global_load_dwordx4 v[168:171], v[90:91], off offset:512
	global_load_dwordx4 v[172:175], v[92:93], off offset:512
	global_load_dwordx4 v[176:179], v[94:95], off offset:512
	ds_read_b128 v[180:183], v124 offset:16
	ds_read_b128 v[184:187], v124 offset:48
	ds_read_b128 v[190:193], v124 offset:4624
	ds_read_b128 v[194:197], v124 offset:4656
	ds_read_b128 v[198:201], v126 offset:36880
	ds_read_b128 v[202:205], v126 offset:36912
	ds_read_b128 v[206:209], v126 offset:41488
	ds_read_b128 v[210:213], v126 offset:41520
	s_waitcnt lgkmcnt(1)
	v_mfma_f32_32x32x16_bf16 v[2:17], v[206:209], v[190:193], v[2:17]
	v_mfma_f32_32x32x16_bf16 v[50:65], v[198:201], v[180:183], v[50:65]
	v_mfma_f32_32x32x16_bf16 v[34:49], v[206:209], v[180:183], v[34:49]
	v_mfma_f32_32x32x16_bf16 v[18:33], v[198:201], v[190:193], v[18:33]
	ds_read_b128 v[180:183], v124 offset:80
	ds_read_b128 v[190:193], v124 offset:4688
	ds_read_b128 v[198:201], v126 offset:36944
	ds_read_b128 v[206:209], v126 offset:41552
	s_waitcnt lgkmcnt(4)
	v_mfma_f32_32x32x16_bf16 v[2:17], v[210:213], v[194:197], v[2:17]
	v_mfma_f32_32x32x16_bf16 v[50:65], v[202:205], v[184:187], v[50:65]
	v_mfma_f32_32x32x16_bf16 v[34:49], v[210:213], v[184:187], v[34:49]
	v_mfma_f32_32x32x16_bf16 v[18:33], v[202:205], v[194:197], v[18:33]
	ds_read_b128 v[184:187], v124 offset:112
	ds_read_b128 v[194:197], v124 offset:4720
	ds_read_b128 v[202:205], v126 offset:36976
	ds_read_b128 v[210:213], v126 offset:41584
	s_waitcnt lgkmcnt(4)
	v_mfma_f32_32x32x16_bf16 v[2:17], v[206:209], v[190:193], v[2:17]
	v_mfma_f32_32x32x16_bf16 v[50:65], v[198:201], v[180:183], v[50:65]
	v_mfma_f32_32x32x16_bf16 v[34:49], v[206:209], v[180:183], v[34:49]
	v_mfma_f32_32x32x16_bf16 v[18:33], v[198:201], v[190:193], v[18:33]
	s_waitcnt lgkmcnt(0)
	v_mfma_f32_32x32x16_bf16 v[2:17], v[210:213], v[194:197], v[2:17]
	v_mfma_f32_32x32x16_bf16 v[50:65], v[202:205], v[184:187], v[50:65]
	v_mfma_f32_32x32x16_bf16 v[34:49], v[210:213], v[184:187], v[34:49]
	v_mfma_f32_32x32x16_bf16 v[18:33], v[202:205], v[194:197], v[18:33]
	s_waitcnt vmcnt(15)
	ds_write_b128 v121, v[96:99] offset:18448
	s_waitcnt vmcnt(14)
	ds_write_b128 v121, v[100:103] offset:55312
	s_waitcnt vmcnt(13)
	ds_write_b128 v121, v[104:107] offset:23056
	s_waitcnt vmcnt(12)
	ds_write_b128 v121, v[108:111] offset:59920
	s_waitcnt vmcnt(11)
	ds_write_b128 v121, v[112:115] offset:27664
	s_waitcnt vmcnt(10)
	ds_write_b128 v121, v[116:119] offset:64528
	s_waitcnt vmcnt(9)
	ds_write_b128 v121, v[140:143] offset:32272
	s_waitcnt vmcnt(8)
	ds_write_b128 v122, v[144:147] offset:32256
	s_waitcnt lgkmcnt(0)
	s_barrier
; template <bool SWAP, class Epi>
; DI void gemm_tile(const u16* __restrict__ A, int lda, const u16* __restrict__ Bt, int ldb, int K, int m0, int n0, char* smem, Epi&& epi) {
;     ...
;   for (int kt = 0; kt < KT; kt += 2) {
;     if (kt + 2 < KT) {
;       const int k0 = (kt + 2) << 6;
; #pragma unroll
;       for (int i = 0; i < 4; ++i) { ra0[i] = *(const u32x4*)(ag + (size_t)i * 32 * lda + k0); rb0[i] = *(const u32x4*)(bg + (size_t)i * 32 * ldb + k0); }
;     }
;     compute(0);
; #pragma unroll
;     for (int i = 0; i < 4; ++i) { *(u32x4*)(asw + 128 * 72 + 32 * i * 72) = ra1[i]; *(u32x4*)(bsw + 128 * 72 + 32 * i * 72) = rb1[i]; }
;     __syncthreads();
;     if (kt + 3 < KT) {
;       const int k0 = (kt + 3) << 6;
; #pragma unroll
;       for (int i = 0; i < 4; ++i) { ra1[i] = *(const u32x4*)(ag + (size_t)i * 32 * lda + k0); rb1[i] = *(const u32x4*)(bg + (size_t)i * 32 * ldb + k0); }
;     }
;     compute(1);
;     if (kt + 2 < KT) {
; #pragma unroll
;       for (int i = 0; i < 4; ++i) { *(u32x4*)(asw + 32 * i * 72) = ra0[i]; *(u32x4*)(bsw + 32 * i * 72) = rb0[i]; }
;     }
;     __syncthreads();
	global_load_dwordx4 v[96:99], v[80:81], off offset:640
	global_load_dwordx4 v[100:103], v[82:83], off offset:640
	global_load_dwordx4 v[104:107], v[84:85], off offset:640
	global_load_dwordx4 v[108:111], v[86:87], off offset:640
	global_load_dwordx4 v[112:115], v[88:89], off offset:640
	global_load_dwordx4 v[116:119], v[90:91], off offset:640
	global_load_dwordx4 v[140:143], v[92:93], off offset:640
	global_load_dwordx4 v[144:147], v[94:95], off offset:640
	ds_read_b128 v[180:183], v124 offset:18448
	ds_read_b128 v[184:187], v124 offset:18480
	ds_read_b128 v[190:193], v124 offset:23056
	ds_read_b128 v[194:197], v124 offset:23088
	ds_read_b128 v[198:201], v126 offset:55312
	ds_read_b128 v[202:205], v126 offset:55344
	ds_read_b128 v[206:209], v126 offset:59920
	ds_read_b128 v[210:213], v126 offset:59952
	s_waitcnt lgkmcnt(1)
	v_mfma_f32_32x32x16_bf16 v[2:17], v[206:209], v[190:193], v[2:17]
	v_mfma_f32_32x32x16_bf16 v[50:65], v[198:201], v[180:183], v[50:65]
	v_mfma_f32_32x32x16_bf16 v[34:49], v[206:209], v[180:183], v[34:49]
	v_mfma_f32_32x32x16_bf16 v[18:33], v[198:201], v[190:193], v[18:33]
	ds_read_b128 v[180:183], v124 offset:18512
	ds_read_b128 v[190:193], v124 offset:23120
	ds_read_b128 v[198:201], v126 offset:55376
	ds_read_b128 v[206:209], v126 offset:59984
	s_waitcnt lgkmcnt(4)
	v_mfma_f32_32x32x16_bf16 v[2:17], v[210:213], v[194:197], v[2:17]
	v_mfma_f32_32x32x16_bf16 v[50:65], v[202:205], v[184:187], v[50:65]
	v_mfma_f32_32x32x16_bf16 v[34:49], v[210:213], v[184:187], v[34:49]
	v_mfma_f32_32x32x16_bf16 v[18:33], v[202:205], v[194:197], v[18:33]
	ds_read_b128 v[184:187], v124 offset:18544
	ds_read_b128 v[194:197], v124 offset:23152
	ds_read_b128 v[202:205], v126 offset:55408
	ds_read_b128 v[210:213], v126 offset:60016
	s_waitcnt lgkmcnt(4)
	v_mfma_f32_32x32x16_bf16 v[2:17], v[206:209], v[190:193], v[2:17]
	v_mfma_f32_32x32x16_bf16 v[50:65], v[198:201], v[180:183], v[50:65]
	v_mfma_f32_32x32x16_bf16 v[34:49], v[206:209], v[180:183], v[34:49]
	v_mfma_f32_32x32x16_bf16 v[18:33], v[198:201], v[190:193], v[18:33]
	s_waitcnt lgkmcnt(0)
	v_mfma_f32_32x32x16_bf16 v[2:17], v[210:213], v[194:197], v[2:17]
	v_mfma_f32_32x32x16_bf16 v[50:65], v[202:205], v[184:187], v[50:65]
	v_mfma_f32_32x32x16_bf16 v[34:49], v[210:213], v[184:187], v[34:49]
	v_mfma_f32_32x32x16_bf16 v[18:33], v[202:205], v[194:197], v[18:33]
	s_waitcnt vmcnt(15)
	ds_write_b128 v121, v[148:151] offset:16
	s_waitcnt vmcnt(14)
	ds_write_b128 v121, v[152:155] offset:36880
	s_waitcnt vmcnt(13)
	ds_write_b128 v121, v[156:159] offset:4624
	s_waitcnt vmcnt(12)
	ds_write_b128 v121, v[160:163] offset:41488
	s_waitcnt vmcnt(11)
	ds_write_b128 v121, v[164:167] offset:9232
	s_waitcnt vmcnt(10)
	ds_write_b128 v121, v[168:171] offset:46096
	s_waitcnt vmcnt(9)
	ds_write_b128 v121, v[172:175] offset:13840
	s_waitcnt vmcnt(8)
	ds_write_b128 v121, v[176:179] offset:50704
	s_waitcnt lgkmcnt(0)
	s_barrier
	global_load_dwordx4 v[148:151], v[80:81], off offset:768
	global_load_dwordx4 v[152:155], v[82:83], off offset:768
	global_load_dwordx4 v[156:159], v[84:85], off offset:768
	global_load_dwordx4 v[160:163], v[86:87], off offset:768
	global_load_dwordx4 v[164:167], v[88:89], off offset:768
	global_load_dwordx4 v[168:171], v[90:91], off offset:768
	global_load_dwordx4 v[172:175], v[92:93], off offset:768
	global_load_dwordx4 v[176:179], v[94:95], off offset:768
	ds_read_b128 v[180:183], v124 offset:16
	ds_read_b128 v[184:187], v124 offset:48
	ds_read_b128 v[190:193], v124 offset:4624
	ds_read_b128 v[194:197], v124 offset:4656
	ds_read_b128 v[198:201], v126 offset:36880
	ds_read_b128 v[202:205], v126 offset:36912
	ds_read_b128 v[206:209], v126 offset:41488
	ds_read_b128 v[210:213], v126 offset:41520
	s_waitcnt lgkmcnt(1)
	v_mfma_f32_32x32x16_bf16 v[2:17], v[206:209], v[190:193], v[2:17]
	v_mfma_f32_32x32x16_bf16 v[50:65], v[198:201], v[180:183], v[50:65]
	v_mfma_f32_32x32x16_bf16 v[34:49], v[206:209], v[180:183], v[34:49]
	v_mfma_f32_32x32x16_bf16 v[18:33], v[198:201], v[190:193], v[18:33]
	ds_read_b128 v[180:183], v124 offset:80
	ds_read_b128 v[190:193], v124 offset:4688
	ds_read_b128 v[198:201], v126 offset:36944
	ds_read_b128 v[206:209], v126 offset:41552
	s_waitcnt lgkmcnt(4)
	v_mfma_f32_32x32x16_bf16 v[2:17], v[210:213], v[194:197], v[2:17]
	v_mfma_f32_32x32x16_bf16 v[50:65], v[202:205], v[184:187], v[50:65]
	v_mfma_f32_32x32x16_bf16 v[34:49], v[210:213], v[184:187], v[34:49]
	v_mfma_f32_32x32x16_bf16 v[18:33], v[202:205], v[194:197], v[18:33]
	ds_read_b128 v[184:187], v124 offset:112
	ds_read_b128 v[194:197], v124 offset:4720
	ds_read_b128 v[202:205], v126 offset:36976
	ds_read_b128 v[210:213], v126 offset:41584
	s_waitcnt lgkmcnt(4)
	v_mfma_f32_32x32x16_bf16 v[2:17], v[206:209], v[190:193], v[2:17]
	v_mfma_f32_32x32x16_bf16 v[50:65], v[198:201], v[180:183], v[50:65]
	v_mfma_f32_32x32x16_bf16 v[34:49], v[206:209], v[180:183], v[34:49]
	v_mfma_f32_32x32x16_bf16 v[18:33], v[198:201], v[190:193], v[18:33]
	s_waitcnt lgkmcnt(0)
	v_mfma_f32_32x32x16_bf16 v[2:17], v[210:213], v[194:197], v[2:17]
	v_mfma_f32_32x32x16_bf16 v[50:65], v[202:205], v[184:187], v[50:65]
	v_mfma_f32_32x32x16_bf16 v[34:49], v[210:213], v[184:187], v[34:49]
	v_mfma_f32_32x32x16_bf16 v[18:33], v[202:205], v[194:197], v[18:33]
	s_waitcnt vmcnt(15)
	ds_write_b128 v121, v[96:99] offset:18448
	s_waitcnt vmcnt(14)
	ds_write_b128 v121, v[100:103] offset:55312
	s_waitcnt vmcnt(13)
	ds_write_b128 v121, v[104:107] offset:23056
	s_waitcnt vmcnt(12)
	ds_write_b128 v121, v[108:111] offset:59920
	s_waitcnt vmcnt(11)
	ds_write_b128 v121, v[112:115] offset:27664
	s_waitcnt vmcnt(10)
	ds_write_b128 v121, v[116:119] offset:64528
	s_waitcnt vmcnt(9)
	ds_write_b128 v121, v[140:143] offset:32272
	s_waitcnt vmcnt(8)
	ds_write_b128 v122, v[144:147] offset:32256
	s_waitcnt lgkmcnt(0)
	s_barrier
; #define MFMA(a, b, c) __builtin_amdgcn_mfma_f32_32x32x16_bf16((a), (b), (c), 0, 0, 0)
; template <bool SWAP, class Epi>
; DI void gemm_tile(const u16* __restrict__ A, int lda, const u16* __restrict__ Bt, int ldb, int K, int m0, int n0, char* smem, Epi&& epi) {
;     ...
;   auto compute = [&](int buf) __attribute__((always_inline)) {
;     bf16x8 af[2][2], bfr[2][2];
;     af[0][0] = *(const bf16x8*)(Asb + buf * 128 * 72);
;     af[0][1] = *(const bf16x8*)(Asb + buf * 128 * 72 + 32 * 72);
;     bfr[0][0] = *(const bf16x8*)(Bsb + buf * 128 * 72);
;     bfr[0][1] = *(const bf16x8*)(Bsb + buf * 128 * 72 + 32 * 72);
; #pragma unroll
;     for (int ks = 0; ks < 4; ++ks) {
;       const int c = ks & 1, n = c ^ 1;
;       if (ks < 3) {
;         af[n][0] = *(const bf16x8*)(Asb + buf * 128 * 72 + (ks + 1) * 16);
;         af[n][1] = *(const bf16x8*)(Asb + buf * 128 * 72 + 32 * 72 + (ks + 1) * 16);
;         bfr[n][0] = *(const bf16x8*)(Bsb + buf * 128 * 72 + (ks + 1) * 16);
;         bfr[n][1] = *(const bf16x8*)(Bsb + buf * 128 * 72 + 32 * 72 + (ks + 1) * 16);
;       }
;       __builtin_amdgcn_sched_barrier(0);
; #pragma unroll
;       for (int mi = 0; mi < 2; ++mi)
; #pragma unroll
;         for (int ni = 0; ni < 2; ++ni) {
;           if (SWAP) acc[mi][ni] = MFMA(bfr[c][ni], af[c][mi], acc[mi][ni]);
;           else acc[mi][ni] = MFMA(af[c][mi], bfr[c][ni], acc[mi][ni]);
;         }
;       __builtin_amdgcn_sched_barrier(0);
;     }
;   };
;   for (int kt = 0; kt < KT; kt += 2) {
;     if (kt + 2 < KT) {
;       const int k0 = (kt + 2) << 6;
; #pragma unroll
;       for (int i = 0; i < 4; ++i) { ra0[i] = *(const u32x4*)(ag + (size_t)i * 32 * lda + k0); rb0[i] = *(const u32x4*)(bg + (size_t)i * 32 * ldb + k0); }
;     }
;     compute(0);
; #pragma unroll
;     for (int i = 0; i < 4; ++i) { *(u32x4*)(asw + 128 * 72 + 32 * i * 72) = ra1[i]; *(u32x4*)(bsw + 128 * 72 + 32 * i * 72) = rb1[i]; }
;     __syncthreads();
;     if (kt + 3 < KT) {
;       const int k0 = (kt + 3) << 6;
; #pragma unroll
;       for (int i = 0; i < 4; ++i) { ra1[i] = *(const u32x4*)(ag + (size_t)i * 32 * lda + k0); rb1[i] = *(const u32x4*)(bg + (size_t)i * 32 * ldb + k0); }
;     }
;     compute(1);
;     if (kt + 2 < KT) {
; #pragma unroll
;       for (int i = 0; i < 4; ++i) { *(u32x4*)(asw + 32 * i * 72) = ra0[i]; *(u32x4*)(bsw + 32 * i * 72) = rb0[i]; }
;     }
;     __syncthreads();
	global_load_dwordx4 v[96:99], v[80:81], off offset:896
	s_nop 0
	global_load_dwordx4 v[80:83], v[82:83], off offset:896
	s_nop 0
	global_load_dwordx4 v[100:103], v[84:85], off offset:896
	s_nop 0
	global_load_dwordx4 v[84:87], v[86:87], off offset:896
	s_nop 0
	global_load_dwordx4 v[104:107], v[88:89], off offset:896
	s_nop 0
	global_load_dwordx4 v[88:91], v[90:91], off offset:896
	s_nop 0
	global_load_dwordx4 v[108:111], v[92:93], off offset:896
	s_nop 0
	global_load_dwordx4 v[92:95], v[94:95], off offset:896
	ds_read_b128 v[112:115], v124 offset:18448
	ds_read_b128 v[116:119], v124 offset:18480
	ds_read_b128 v[140:143], v124 offset:23056
	ds_read_b128 v[144:147], v124 offset:23088
	ds_read_b128 v[180:183], v126 offset:55312
	ds_read_b128 v[184:187], v126 offset:55344
	ds_read_b128 v[190:193], v126 offset:59920
	ds_read_b128 v[194:197], v126 offset:59952
	s_waitcnt lgkmcnt(1)
	v_mfma_f32_32x32x16_bf16 v[2:17], v[190:193], v[140:143], v[2:17]
	v_mfma_f32_32x32x16_bf16 v[50:65], v[180:183], v[112:115], v[50:65]
	v_mfma_f32_32x32x16_bf16 v[34:49], v[190:193], v[112:115], v[34:49]
	v_mfma_f32_32x32x16_bf16 v[18:33], v[180:183], v[140:143], v[18:33]
	ds_read_b128 v[112:115], v124 offset:18512
	ds_read_b128 v[140:143], v124 offset:23120
	ds_read_b128 v[180:183], v126 offset:55376
	ds_read_b128 v[190:193], v126 offset:59984
	s_waitcnt lgkmcnt(4)
	v_mfma_f32_32x32x16_bf16 v[2:17], v[194:197], v[144:147], v[2:17]
	v_mfma_f32_32x32x16_bf16 v[50:65], v[184:187], v[116:119], v[50:65]
	v_mfma_f32_32x32x16_bf16 v[34:49], v[194:197], v[116:119], v[34:49]
	v_mfma_f32_32x32x16_bf16 v[18:33], v[184:187], v[144:147], v[18:33]
	ds_read_b128 v[116:119], v124 offset:18544
	ds_read_b128 v[144:147], v124 offset:23152
	ds_read_b128 v[184:187], v126 offset:55408
	ds_read_b128 v[194:197], v126 offset:60016
	s_waitcnt lgkmcnt(4)
	v_mfma_f32_32x32x16_bf16 v[2:17], v[190:193], v[140:143], v[2:17]
	v_mfma_f32_32x32x16_bf16 v[50:65], v[180:183], v[112:115], v[50:65]
	v_mfma_f32_32x32x16_bf16 v[34:49], v[190:193], v[112:115], v[34:49]
	v_mfma_f32_32x32x16_bf16 v[18:33], v[180:183], v[140:143], v[18:33]
	s_waitcnt lgkmcnt(0)
	v_mfma_f32_32x32x16_bf16 v[2:17], v[194:197], v[144:147], v[2:17]
	v_mfma_f32_32x32x16_bf16 v[50:65], v[184:187], v[116:119], v[50:65]
	v_mfma_f32_32x32x16_bf16 v[34:49], v[194:197], v[116:119], v[34:49]
	v_mfma_f32_32x32x16_bf16 v[18:33], v[184:187], v[144:147], v[18:33]
	s_waitcnt vmcnt(15)
	ds_write_b128 v121, v[148:151] offset:16
	s_waitcnt vmcnt(14)
	ds_write_b128 v121, v[152:155] offset:36880
	s_waitcnt vmcnt(13)
	ds_write_b128 v121, v[156:159] offset:4624
	s_waitcnt vmcnt(12)
	ds_write_b128 v121, v[160:163] offset:41488
	s_waitcnt vmcnt(11)
	ds_write_b128 v121, v[164:167] offset:9232
	s_waitcnt vmcnt(10)
	ds_write_b128 v121, v[168:171] offset:46096
	s_waitcnt vmcnt(9)
	ds_write_b128 v121, v[172:175] offset:13840
	s_waitcnt vmcnt(8)
	ds_write_b128 v121, v[176:179] offset:50704
	s_waitcnt lgkmcnt(0)
	s_barrier
	ds_read_b128 v[112:115], v124 offset:16
	ds_read_b128 v[116:119], v124 offset:48
	ds_read_b128 v[140:143], v124 offset:4624
	ds_read_b128 v[144:147], v124 offset:4656
	ds_read_b128 v[148:151], v126 offset:36880
	ds_read_b128 v[152:155], v126 offset:36912
	ds_read_b128 v[156:159], v126 offset:41488
	ds_read_b128 v[160:163], v126 offset:41520
	s_waitcnt lgkmcnt(1)
	v_mfma_f32_32x32x16_bf16 v[2:17], v[156:159], v[140:143], v[2:17]
	v_mfma_f32_32x32x16_bf16 v[50:65], v[148:151], v[112:115], v[50:65]
	v_mfma_f32_32x32x16_bf16 v[34:49], v[156:159], v[112:115], v[34:49]
	v_mfma_f32_32x32x16_bf16 v[18:33], v[148:151], v[140:143], v[18:33]
	ds_read_b128 v[112:115], v124 offset:80
	ds_read_b128 v[140:143], v124 offset:4688
	ds_read_b128 v[148:151], v126 offset:36944
	ds_read_b128 v[156:159], v126 offset:41552
	s_waitcnt lgkmcnt(4)
	v_mfma_f32_32x32x16_bf16 v[2:17], v[160:163], v[144:147], v[2:17]
	v_mfma_f32_32x32x16_bf16 v[50:65], v[152:155], v[116:119], v[50:65]
	v_mfma_f32_32x32x16_bf16 v[34:49], v[160:163], v[116:119], v[34:49]
	v_mfma_f32_32x32x16_bf16 v[18:33], v[152:155], v[144:147], v[18:33]
	ds_read_b128 v[116:119], v124 offset:112
	ds_read_b128 v[144:147], v124 offset:4720
	ds_read_b128 v[152:155], v126 offset:36976
	ds_read_b128 v[160:163], v126 offset:41584
	s_waitcnt lgkmcnt(4)
	v_mfma_f32_32x32x16_bf16 v[2:17], v[156:159], v[140:143], v[2:17]
	v_mfma_f32_32x32x16_bf16 v[50:65], v[148:151], v[112:115], v[50:65]
	v_mfma_f32_32x32x16_bf16 v[34:49], v[156:159], v[112:115], v[34:49]
	v_mfma_f32_32x32x16_bf16 v[18:33], v[148:151], v[140:143], v[18:33]
	s_waitcnt lgkmcnt(0)
	v_mfma_f32_32x32x16_bf16 v[2:17], v[160:163], v[144:147], v[2:17]
	v_mfma_f32_32x32x16_bf16 v[50:65], v[152:155], v[116:119], v[50:65]
	v_mfma_f32_32x32x16_bf16 v[34:49], v[160:163], v[116:119], v[34:49]
	v_mfma_f32_32x32x16_bf16 v[18:33], v[152:155], v[144:147], v[18:33]
	s_waitcnt vmcnt(7)
	ds_write_b128 v121, v[96:99] offset:18448
	s_waitcnt vmcnt(6)
	ds_write_b128 v121, v[80:83] offset:55312
	s_waitcnt vmcnt(5)
	ds_write_b128 v121, v[100:103] offset:23056
	s_waitcnt vmcnt(4)
	ds_write_b128 v121, v[84:87] offset:59920
	s_waitcnt vmcnt(3)
	ds_write_b128 v121, v[104:107] offset:27664
	s_waitcnt vmcnt(2)
	ds_write_b128 v121, v[88:91] offset:64528
	s_waitcnt vmcnt(1)
	ds_write_b128 v121, v[108:111] offset:32272
	s_waitcnt vmcnt(0)
	ds_write_b128 v122, v[92:95] offset:32256
	s_waitcnt lgkmcnt(0)
	s_barrier
; #define MFMA(a, b, c) __builtin_amdgcn_mfma_f32_32x32x16_bf16((a), (b), (c), 0, 0, 0)
; template <bool SWAP, class Epi>
; DI void gemm_tile(const u16* __restrict__ A, int lda, const u16* __restrict__ Bt, int ldb, int K, int m0, int n0, char* smem, Epi&& epi) {
;     ...
;   auto compute = [&](int buf) __attribute__((always_inline)) {
;     bf16x8 af[2][2], bfr[2][2];
;     af[0][0] = *(const bf16x8*)(Asb + buf * 128 * 72);
;     af[0][1] = *(const bf16x8*)(Asb + buf * 128 * 72 + 32 * 72);
;     bfr[0][0] = *(const bf16x8*)(Bsb + buf * 128 * 72);
;     bfr[0][1] = *(const bf16x8*)(Bsb + buf * 128 * 72 + 32 * 72);
; #pragma unroll
;     for (int ks = 0; ks < 4; ++ks) {
;       const int c = ks & 1, n = c ^ 1;
;       if (ks < 3) {
;         af[n][0] = *(const bf16x8*)(Asb + buf * 128 * 72 + (ks + 1) * 16);
;         af[n][1] = *(const bf16x8*)(Asb + buf * 128 * 72 + 32 * 72 + (ks + 1) * 16);
;         bfr[n][0] = *(const bf16x8*)(Bsb + buf * 128 * 72 + (ks + 1) * 16);
;         bfr[n][1] = *(const bf16x8*)(Bsb + buf * 128 * 72 + 32 * 72 + (ks + 1) * 16);
;       }
;       __builtin_amdgcn_sched_barrier(0);
; #pragma unroll
;       for (int mi = 0; mi < 2; ++mi)
; #pragma unroll
;         for (int ni = 0; ni < 2; ++ni) {
;           if (SWAP) acc[mi][ni] = MFMA(bfr[c][ni], af[c][mi], acc[mi][ni]);
;           else acc[mi][ni] = MFMA(af[c][mi], bfr[c][ni], acc[mi][ni]);
;         }
;       __builtin_amdgcn_sched_barrier(0);
;     }
;   };
; DI void phase3(const Params& p, char* smem) {
;     ...
;         gemm_tile<true>(P + 3584, INC, (const u16*)(p.ws + WS_WUKVT), 512, 512, tm * 128, tn * 128, smem, [&](f32x16 (&acc)[2][2], int mb, int nb, int r, int hi) __attribute__((always_inline)) {
; #pragma unroll
;           for (int mi = 0; mi < 2; ++mi) {
;             const int row = mb + mi * 32 + r;
;             const float sc = rs[row - tm * 128];
; #pragma unroll
;             for (int ni = 0; ni < 2; ++ni)
; #pragma unroll
;               for (int g = 0; g < 4; ++g) {
;                 const int d = (nb & 127) + ni * 32 + hi * 4 + 8 * g;
;                 *(uint2*)(Kb + (size_t)row * 1536 + head * 192 + d) = make_uint2(pk2(acc[mi][ni][4 * g] * sc, acc[mi][ni][4 * g + 1] * sc), pk2(acc[mi][ni][4 * g + 2] * sc, acc[mi][ni][4 * g + 3] * sc));
;               }
;           }
;         });
	ds_read_b128 v[80:83], v124 offset:18448
	ds_read_b128 v[84:87], v124 offset:18480
	ds_read_b128 v[88:91], v124 offset:23056
	ds_read_b128 v[92:95], v124 offset:23088
	ds_read_b128 v[96:99], v126 offset:55312
	ds_read_b128 v[100:103], v126 offset:55344
	ds_read_b128 v[104:107], v126 offset:59920
	ds_read_b128 v[108:111], v126 offset:59952
	s_waitcnt lgkmcnt(1)
	v_mfma_f32_32x32x16_bf16 v[2:17], v[104:107], v[88:91], v[2:17]
	v_mfma_f32_32x32x16_bf16 v[50:65], v[96:99], v[80:83], v[50:65]
	v_mfma_f32_32x32x16_bf16 v[34:49], v[104:107], v[80:83], v[34:49]
	v_mfma_f32_32x32x16_bf16 v[18:33], v[96:99], v[88:91], v[18:33]
	ds_read_b128 v[80:83], v124 offset:18512
	ds_read_b128 v[88:91], v124 offset:23120
	ds_read_b128 v[96:99], v126 offset:55376
	ds_read_b128 v[104:107], v126 offset:59984
	s_waitcnt lgkmcnt(4)
	v_mfma_f32_32x32x16_bf16 v[2:17], v[108:111], v[92:95], v[2:17]
	v_mfma_f32_32x32x16_bf16 v[50:65], v[100:103], v[84:87], v[50:65]
	v_mfma_f32_32x32x16_bf16 v[34:49], v[108:111], v[84:87], v[34:49]
	v_mfma_f32_32x32x16_bf16 v[18:33], v[100:103], v[92:95], v[18:33]
	ds_read_b128 v[84:87], v124 offset:18544
	ds_read_b128 v[92:95], v124 offset:23152
	ds_read_b128 v[100:103], v126 offset:55408
	ds_read_b128 v[108:111], v126 offset:60016
	s_waitcnt lgkmcnt(4)
	v_mfma_f32_32x32x16_bf16 v[2:17], v[104:107], v[88:91], v[2:17]
	v_mfma_f32_32x32x16_bf16 v[50:65], v[96:99], v[80:83], v[50:65]
	v_mfma_f32_32x32x16_bf16 v[34:49], v[104:107], v[80:83], v[34:49]
	v_mfma_f32_32x32x16_bf16 v[18:33], v[96:99], v[88:91], v[18:33]
	s_waitcnt lgkmcnt(0)
	v_mfma_f32_32x32x16_bf16 v[2:17], v[108:111], v[92:95], v[2:17]
	v_mfma_f32_32x32x16_bf16 v[50:65], v[100:103], v[84:87], v[50:65]
	v_mfma_f32_32x32x16_bf16 v[34:49], v[108:111], v[84:87], v[34:49]
	v_mfma_f32_32x32x16_bf16 v[18:33], v[100:103], v[92:95], v[18:33]
	s_barrier
	v_add_u32_e32 v79, s92, v123
	ds_read_b32 v80, v130
	v_mul_u32_u24_e32 v66, 0xc00, v79
	v_or_b32_e32 v79, 32, v79
	v_subrev_u32_e32 v79, s92, v79
	v_lshl_add_u32 v79, v79, 2, 0
	v_add_u32_e32 v79, 0x12010, v79
	ds_read_b32 v82, v79
	v_lshl_add_u64 v[140:141], s[4:5], 0, v[66:67]
	s_mulk_i32 s16, 0xc0
	v_mov_b32_e32 v79, v67
	v_and_b32_e32 v142, 32, v0
	v_lshl_add_u64 v[140:141], s[16:17], 1, v[140:141]
	v_lshrrev_b32_e32 v142, 2, v142
	v_mov_b32_e32 v143, 0
	v_lshl_add_u64 v[140:141], v[140:141], 0, v[78:79]
	v_lshl_add_u64 v[140:141], v[140:141], 0, v[142:143]
	v_lshl_add_u64 v[144:145], v[140:141], 0, s[30:31]
	s_waitcnt lgkmcnt(1)
	v_pk_mul_f32 v[50:51], v[50:51], v[80:81] op_sel_hi:[1,0]
	v_pk_mul_f32 v[52:53], v[52:53], v[80:81] op_sel_hi:[1,0]
	v_pk_mul_f32 v[54:55], v[54:55], v[80:81] op_sel_hi:[1,0]
	v_pk_mul_f32 v[56:57], v[56:57], v[80:81] op_sel_hi:[1,0]
	v_cvt_pk_bf16_f32 v148, v50, v51
	v_cvt_pk_bf16_f32 v149, v52, v53
	v_cvt_pk_bf16_f32 v150, v54, v55
	v_cvt_pk_bf16_f32 v151, v56, v57
	s_nop 1
	v_permlane32_swap_b32_e32 v148, v150
	v_permlane32_swap_b32_e32 v149, v151
	global_store_dwordx4 v[140:141], v[148:151], off
	v_pk_mul_f32 v[58:59], v[58:59], v[80:81] op_sel_hi:[1,0]
	v_pk_mul_f32 v[60:61], v[60:61], v[80:81] op_sel_hi:[1,0]
	v_pk_mul_f32 v[62:63], v[62:63], v[80:81] op_sel_hi:[1,0]
	v_pk_mul_f32 v[64:65], v[64:65], v[80:81] op_sel_hi:[1,0]
	v_cvt_pk_bf16_f32 v152, v58, v59
	v_cvt_pk_bf16_f32 v153, v60, v61
	v_cvt_pk_bf16_f32 v154, v62, v63
	v_cvt_pk_bf16_f32 v155, v64, v65
	s_nop 1
	v_permlane32_swap_b32_e32 v152, v154
	v_permlane32_swap_b32_e32 v153, v155
	global_store_dwordx4 v[140:141], v[152:155], off offset:32
	v_pk_mul_f32 v[34:35], v[34:35], v[80:81] op_sel_hi:[1,0]
	v_pk_mul_f32 v[36:37], v[36:37], v[80:81] op_sel_hi:[1,0]
	v_pk_mul_f32 v[38:39], v[38:39], v[80:81] op_sel_hi:[1,0]
	v_pk_mul_f32 v[40:41], v[40:41], v[80:81] op_sel_hi:[1,0]
	v_cvt_pk_bf16_f32 v148, v34, v35
	v_cvt_pk_bf16_f32 v149, v36, v37
	v_cvt_pk_bf16_f32 v150, v38, v39
	v_cvt_pk_bf16_f32 v151, v40, v41
	s_nop 1
	v_permlane32_swap_b32_e32 v148, v150
	v_permlane32_swap_b32_e32 v149, v151
	global_store_dwordx4 v[140:141], v[148:151], off offset:64
	v_pk_mul_f32 v[42:43], v[42:43], v[80:81] op_sel_hi:[1,0]
	v_pk_mul_f32 v[44:45], v[44:45], v[80:81] op_sel_hi:[1,0]
	v_pk_mul_f32 v[46:47], v[46:47], v[80:81] op_sel_hi:[1,0]
	v_pk_mul_f32 v[48:49], v[48:49], v[80:81] op_sel_hi:[1,0]
	v_cvt_pk_bf16_f32 v152, v42, v43
	v_cvt_pk_bf16_f32 v153, v44, v45
	v_cvt_pk_bf16_f32 v154, v46, v47
	v_cvt_pk_bf16_f32 v155, v48, v49
	s_nop 1
	v_permlane32_swap_b32_e32 v152, v154
	v_permlane32_swap_b32_e32 v153, v155
	global_store_dwordx4 v[140:141], v[152:155], off offset:96
	s_waitcnt lgkmcnt(0)
	v_pk_mul_f32 v[18:19], v[18:19], v[82:83] op_sel_hi:[1,0]
	v_pk_mul_f32 v[20:21], v[20:21], v[82:83] op_sel_hi:[1,0]
	v_pk_mul_f32 v[22:23], v[22:23], v[82:83] op_sel_hi:[1,0]
	v_pk_mul_f32 v[24:25], v[24:25], v[82:83] op_sel_hi:[1,0]
	v_cvt_pk_bf16_f32 v148, v18, v19
	v_cvt_pk_bf16_f32 v149, v20, v21
	v_cvt_pk_bf16_f32 v150, v22, v23
	v_cvt_pk_bf16_f32 v151, v24, v25
	s_nop 1
	v_permlane32_swap_b32_e32 v148, v150
	v_permlane32_swap_b32_e32 v149, v151
	global_store_dwordx4 v[144:145], v[148:151], off
	v_pk_mul_f32 v[26:27], v[26:27], v[82:83] op_sel_hi:[1,0]
	v_pk_mul_f32 v[28:29], v[28:29], v[82:83] op_sel_hi:[1,0]
	v_pk_mul_f32 v[30:31], v[30:31], v[82:83] op_sel_hi:[1,0]
	v_pk_mul_f32 v[32:33], v[32:33], v[82:83] op_sel_hi:[1,0]
	v_cvt_pk_bf16_f32 v152, v26, v27
	v_cvt_pk_bf16_f32 v153, v28, v29
	v_cvt_pk_bf16_f32 v154, v30, v31
	v_cvt_pk_bf16_f32 v155, v32, v33
	s_nop 1
	v_permlane32_swap_b32_e32 v152, v154
	v_permlane32_swap_b32_e32 v153, v155
	global_store_dwordx4 v[144:145], v[152:155], off offset:32
	v_pk_mul_f32 v[2:3], v[2:3], v[82:83] op_sel_hi:[1,0]
	v_pk_mul_f32 v[4:5], v[4:5], v[82:83] op_sel_hi:[1,0]
	v_pk_mul_f32 v[6:7], v[6:7], v[82:83] op_sel_hi:[1,0]
	v_pk_mul_f32 v[8:9], v[8:9], v[82:83] op_sel_hi:[1,0]
	v_cvt_pk_bf16_f32 v148, v2, v3
	v_cvt_pk_bf16_f32 v149, v4, v5
	v_cvt_pk_bf16_f32 v150, v6, v7
	v_cvt_pk_bf16_f32 v151, v8, v9
	s_nop 1
	v_permlane32_swap_b32_e32 v148, v150
	v_permlane32_swap_b32_e32 v149, v151
	global_store_dwordx4 v[144:145], v[148:151], off offset:64
	v_pk_mul_f32 v[10:11], v[10:11], v[82:83] op_sel_hi:[1,0]
	v_pk_mul_f32 v[12:13], v[12:13], v[82:83] op_sel_hi:[1,0]
	v_pk_mul_f32 v[14:15], v[14:15], v[82:83] op_sel_hi:[1,0]
	v_pk_mul_f32 v[16:17], v[16:17], v[82:83] op_sel_hi:[1,0]
	v_cvt_pk_bf16_f32 v152, v10, v11
	v_cvt_pk_bf16_f32 v153, v12, v13
	v_cvt_pk_bf16_f32 v154, v14, v15
	v_cvt_pk_bf16_f32 v155, v16, v17
	s_nop 1
	v_permlane32_swap_b32_e32 v152, v154
	v_permlane32_swap_b32_e32 v153, v155
	global_store_dwordx4 v[144:145], v[152:155], off offset:96
	s_branch .Lp3_next
